# P1 epilogue head-norm sums of squares: pair-building v_mov + v_pk_mul/v_pk_fma replaced by v_mul_f32/v_fma_f32 on the accumulators (same ops and order)
# baseline (speedup 1.0000x reference)
; __device__ __forceinline__ float sq4(f32x4 v) { return (v[0] * v[0] + v[1] * v[1]) + (v[2] * v[2] + v[3] * v[3]); }
;     __device__ __forceinline__ void apply(int row, int cl, const Pre& P_, f32x4 a0, f32x4 a1, f32x4 b0, f32x4 b1) const {
;     ...
;             if (sel < 2) {
;                 float ss = (sq4(a0) + sq4(a1)) + (sq4(b0) + sq4(b1));
;                 ss += __shfl_xor(ss, 16); ss += __shfl_xor(ss, 32);
;                 const float rr = __builtin_amdgcn_rsqf(ss * (1.f / 64.f) + EPS) * (sel == 0 ? 0.125f * LOG2E : 1.f);
;                 const float* gp = qg + sel * (kg - qg) + (cl & 63);
;                 const f32x4 g0 = *(const f32x4*)gp, g1 = *(const f32x4*)(gp + 4), g2 = *(const f32x4*)(gp + 32), g3 = *(const f32x4*)(gp + 36);
;                 a0 = a0 * rr * g0; a1 = a1 * rr * g1; b0 = b0 * rr * g2; b1 = b1 * rr * g3;
.LBB0_171:
	s_andn2_saveexec_b64 s[34:35], s[34:35]
	s_cbranch_execz .LBB0_175
	v_add_u32_e32 v37, 0xfffffe00, v46
	v_lshrrev_b32_e32 v22, 9, v37
	v_cmp_gt_u32_e32 vcc, s49, v37
	s_and_saveexec_b64 s[36:37], vcc
	s_cbranch_execz .LBB0_174
	v_mad_u64_u32 v[48:49], s[64:65], s24, v22, 0
	v_mov_b32_e32 v52, v49
	v_mad_u64_u32 v[52:53], s[64:65], s25, v22, v[52:53]
	v_mov_b32_e32 v49, v52
	v_lshl_add_u64 v[48:49], v[48:49], 2, v[26:27]
	global_load_dwordx4 v[52:55], v[48:49], off
	global_load_dwordx4 v[56:59], v[48:49], off offset:16
	global_load_dwordx4 v[60:63], v[48:49], off offset:128
	global_load_dwordx4 v[64:67], v[48:49], off offset:144
	v_and_b32_e32 v41, 64, v50
	v_mul_f32_e32 v68, v15, v15
	v_mul_f32_e32 v69, v9, v9
	v_mul_f32_e32 v72, v17, v17
	v_mul_f32_e32 v73, v7, v7
	v_mul_f32_e32 v76, v11, v11
	v_mul_f32_e32 v77, v5, v5
	v_mul_f32_e32 v80, v13, v13
	v_mul_f32_e32 v81, v3, v3
	v_xor_b32_e32 v39, 16, v50
	v_add_u32_e32 v41, 64, v41
	v_fma_f32 v48, v14, v14, v68
	v_fma_f32 v49, v8, v8, v69
	v_fma_f32 v68, v16, v16, v72
	v_fma_f32 v69, v6, v6, v73
	v_fma_f32 v70, v10, v10, v76
	v_fma_f32 v71, v4, v4, v77
	v_fma_f32 v72, v12, v12, v80
	v_fma_f32 v73, v2, v2, v81
	v_cmp_lt_i32_e32 vcc, v39, v41
	v_pk_add_f32 v[48:49], v[48:49], v[68:69]
	v_pk_add_f32 v[68:69], v[70:71], v[72:73]
	v_cndmask_b32_e32 v39, v50, v39, vcc
	v_pk_add_f32 v[48:49], v[48:49], v[68:69]
	v_lshlrev_b32_e32 v39, 2, v39
	v_add_f32_e32 v43, v48, v49
	ds_bpermute_b32 v39, v39, v43
	v_xor_b32_e32 v45, 32, v50
	v_cmp_lt_i32_e32 vcc, v45, v41
	s_waitcnt lgkmcnt(0)
	v_add_f32_e32 v39, v43, v39
	v_cndmask_b32_e32 v41, v50, v45, vcc
	v_lshlrev_b32_e32 v41, 2, v41
	ds_bpermute_b32 v41, v41, v39
	v_cmp_gt_u32_e32 vcc, s50, v37
	s_waitcnt lgkmcnt(0)
	v_add_f32_e32 v39, v39, v41
	v_fmamk_f32 v39, v39, 0x3c800000, v19
	v_rsq_f32_e32 v39, v39
	v_cndmask_b32_e32 v37, 1.0, v51, vcc
	v_mul_f32_e32 v48, v37, v39
	v_pk_mul_f32 v[14:15], v[14:15], v[48:49] op_sel_hi:[1,0]
	v_pk_mul_f32 v[16:17], v[16:17], v[48:49] op_sel_hi:[1,0]
	v_pk_mul_f32 v[10:11], v[10:11], v[48:49] op_sel_hi:[1,0]
	v_pk_mul_f32 v[12:13], v[12:13], v[48:49] op_sel_hi:[1,0]
	v_pk_mul_f32 v[8:9], v[8:9], v[48:49] op_sel_hi:[1,0]
	v_pk_mul_f32 v[6:7], v[6:7], v[48:49] op_sel_hi:[1,0]
	v_pk_mul_f32 v[4:5], v[4:5], v[48:49] op_sel_hi:[1,0]
	v_pk_mul_f32 v[2:3], v[2:3], v[48:49] op_sel_hi:[1,0]
	s_waitcnt vmcnt(3)
	v_pk_mul_f32 v[16:17], v[54:55], v[16:17]
	v_pk_mul_f32 v[14:15], v[52:53], v[14:15]
	s_waitcnt vmcnt(2)
	v_pk_mul_f32 v[12:13], v[58:59], v[12:13]
	v_pk_mul_f32 v[10:11], v[56:57], v[10:11]
	s_waitcnt vmcnt(1)
	v_pk_mul_f32 v[6:7], v[62:63], v[6:7]
	v_pk_mul_f32 v[8:9], v[60:61], v[8:9]
	s_waitcnt vmcnt(0)
	v_pk_mul_f32 v[2:3], v[66:67], v[2:3]
	v_pk_mul_f32 v[4:5], v[64:65], v[4:5]

; __device__ __forceinline__ float sq4(f32x4 v) { return (v[0] * v[0] + v[1] * v[1]) + (v[2] * v[2] + v[3] * v[3]); }
;     __device__ __forceinline__ void apply(int row, int cl, const Pre& P_, f32x4 a0, f32x4 a1, f32x4 b0, f32x4 b1) const {
;     ...
;             if (sel < 2) {
;                 float ss = (sq4(a0) + sq4(a1)) + (sq4(b0) + sq4(b1));
;                 ss += __shfl_xor(ss, 16); ss += __shfl_xor(ss, 32);
;                 const float rr = __builtin_amdgcn_rsqf(ss * (1.f / 64.f) + EPS) * (sel == 0 ? 0.125f * LOG2E : 1.f);
;                 const float* gp = qg + sel * (kg - qg) + (cl & 63);
;                 const f32x4 g0 = *(const f32x4*)gp, g1 = *(const f32x4*)(gp + 4), g2 = *(const f32x4*)(gp + 32), g3 = *(const f32x4*)(gp + 36);
;                 a0 = a0 * rr * g0; a1 = a1 * rr * g1; b0 = b0 * rr * g2; b1 = b1 * rr * g3;
.LBB0_203:
	s_andn2_b64 vcc, exec, s[10:11]
	s_cbranch_vccnz .LBB0_210
	v_mov_b64_e32 v[136:137], v[116:117]
	v_mov_b64_e32 v[132:133], v[120:121]
	v_mov_b64_e32 v[140:141], v[124:125]
	v_mov_b64_e32 v[144:145], v[128:129]
	v_mov_b64_e32 v[134:135], v[114:115]
	v_mov_b64_e32 v[130:131], v[118:119]
	v_mov_b64_e32 v[138:139], v[122:123]
	v_mov_b64_e32 v[142:143], v[126:127]
	s_and_saveexec_b64 s[10:11], s[6:7]
	s_cbranch_execz .LBB0_206
	v_mad_u64_u32 v[130:131], s[12:13], s28, v189, 0
	v_mov_b32_e32 v132, v131
	v_mad_u64_u32 v[132:133], s[12:13], s29, v189, v[132:133]
	v_mov_b32_e32 v131, v132
	v_lshl_add_u64 v[138:139], v[130:131], 2, v[156:157]
	global_load_dwordx4 v[130:133], v[138:139], off
	global_load_dwordx4 v[134:137], v[138:139], off offset:16
	global_load_dwordx4 v[192:195], v[138:139], off offset:128
	global_load_dwordx4 v[196:199], v[138:139], off offset:144
	v_and_b32_e32 v191, 64, v186
	v_mul_f32_e32 v140, v127, v127
	v_mul_f32_e32 v141, v119, v119
	v_mul_f32_e32 v144, v129, v129
	v_mul_f32_e32 v145, v121, v121
	v_mul_f32_e32 v200, v123, v123
	v_mul_f32_e32 v201, v115, v115
	v_mul_f32_e32 v204, v125, v125
	v_mul_f32_e32 v205, v117, v117
	v_xor_b32_e32 v171, 16, v186
	v_add_u32_e32 v191, 64, v191
	v_fma_f32 v138, v126, v126, v140
	v_fma_f32 v139, v118, v118, v141
	v_fma_f32 v140, v128, v128, v144
	v_fma_f32 v141, v120, v120, v145
	v_fma_f32 v142, v122, v122, v200
	v_fma_f32 v143, v114, v114, v201
	v_fma_f32 v144, v124, v124, v204
	v_fma_f32 v145, v116, v116, v205
	v_cmp_lt_i32_e32 vcc, v171, v191
	v_pk_add_f32 v[138:139], v[138:139], v[140:141]
	v_pk_add_f32 v[140:141], v[142:143], v[144:145]
	v_cndmask_b32_e32 v171, v186, v171, vcc
	v_pk_add_f32 v[138:139], v[138:139], v[140:141]
	v_lshlrev_b32_e32 v142, 2, v171
	v_add_f32_e32 v138, v138, v139
	ds_bpermute_b32 v139, v142, v138
	v_xor_b32_e32 v140, 32, v186
	v_cmp_lt_i32_e32 vcc, v140, v191
	s_waitcnt lgkmcnt(0)
	v_add_f32_e32 v138, v138, v139
	v_cndmask_b32_e32 v140, v186, v140, vcc
	v_lshlrev_b32_e32 v140, 2, v140
	ds_bpermute_b32 v139, v140, v138
	s_waitcnt lgkmcnt(0)
	v_add_f32_e32 v138, v138, v139
	v_fmamk_f32 v138, v138, 0x3c800000, v183
	v_rsq_f32_e32 v138, v138
	s_nop 0
	v_mul_f32_e32 v138, v188, v138
	v_pk_mul_f32 v[140:141], v[126:127], v[138:139] op_sel_hi:[1,0]
	v_pk_mul_f32 v[142:143], v[128:129], v[138:139] op_sel_hi:[1,0]
	v_pk_mul_f32 v[178:179], v[122:123], v[138:139] op_sel_hi:[1,0]
	v_pk_mul_f32 v[200:201], v[124:125], v[138:139] op_sel_hi:[1,0]
	v_pk_mul_f32 v[202:203], v[118:119], v[138:139] op_sel_hi:[1,0]
	v_pk_mul_f32 v[204:205], v[120:121], v[138:139] op_sel_hi:[1,0]
	v_pk_mul_f32 v[206:207], v[114:115], v[138:139] op_sel_hi:[1,0]
	v_pk_mul_f32 v[208:209], v[116:117], v[138:139] op_sel_hi:[1,0]
	s_waitcnt vmcnt(3)
	v_pk_mul_f32 v[144:145], v[132:133], v[142:143]
	v_pk_mul_f32 v[142:143], v[130:131], v[140:141]
	s_waitcnt vmcnt(2)
	v_pk_mul_f32 v[140:141], v[136:137], v[200:201]
	v_pk_mul_f32 v[138:139], v[134:135], v[178:179]
	s_waitcnt vmcnt(1)
	v_pk_mul_f32 v[132:133], v[194:195], v[204:205]
	v_pk_mul_f32 v[130:131], v[192:193], v[202:203]
	s_waitcnt vmcnt(0)
	v_pk_mul_f32 v[136:137], v[198:199], v[208:209]
	v_pk_mul_f32 v[134:135], v[196:197], v[206:207]

; __device__ __forceinline__ float sq4(f32x4 v) { return (v[0] * v[0] + v[1] * v[1]) + (v[2] * v[2] + v[3] * v[3]); }
;     __device__ __forceinline__ void apply(int row, int cl, const Pre& P_, f32x4 a0, f32x4 a1, f32x4 b0, f32x4 b1) const {
;     ...
;             if (sel < 2) {
;                 float ss = (sq4(a0) + sq4(a1)) + (sq4(b0) + sq4(b1));
;                 ss += __shfl_xor(ss, 16); ss += __shfl_xor(ss, 32);
;                 const float rr = __builtin_amdgcn_rsqf(ss * (1.f / 64.f) + EPS) * (sel == 0 ? 0.125f * LOG2E : 1.f);
;                 const float* gp = qg + sel * (kg - qg) + (cl & 63);
;                 const f32x4 g0 = *(const f32x4*)gp, g1 = *(const f32x4*)(gp + 4), g2 = *(const f32x4*)(gp + 32), g3 = *(const f32x4*)(gp + 36);
;                 a0 = a0 * rr * g0; a1 = a1 * rr * g1; b0 = b0 * rr * g2; b1 = b1 * rr * g3;
.LBB0_219:
	s_andn2_b64 vcc, exec, s[46:47]
	s_cbranch_vccnz .LBB0_226
	v_mov_b64_e32 v[120:121], v[100:101]
	v_mov_b64_e32 v[116:117], v[104:105]
	v_mov_b64_e32 v[124:125], v[108:109]
	v_mov_b64_e32 v[128:129], v[112:113]
	v_mov_b64_e32 v[118:119], v[98:99]
	v_mov_b64_e32 v[114:115], v[102:103]
	v_mov_b64_e32 v[122:123], v[106:107]
	v_mov_b64_e32 v[126:127], v[110:111]
	s_and_saveexec_b64 s[46:47], s[6:7]
	s_cbranch_execz .LBB0_222
	v_mad_u64_u32 v[114:115], s[38:39], s28, v189, 0
	v_mov_b32_e32 v116, v115
	v_mad_u64_u32 v[116:117], s[38:39], s29, v189, v[116:117]
	v_mov_b32_e32 v115, v116
	v_lshl_add_u64 v[122:123], v[114:115], 2, v[156:157]
	global_load_dwordx4 v[114:117], v[122:123], off
	global_load_dwordx4 v[118:121], v[122:123], off offset:16
	global_load_dwordx4 v[134:137], v[122:123], off offset:128
	global_load_dwordx4 v[138:141], v[122:123], off offset:144
	v_and_b32_e32 v176, 64, v186
	v_mul_f32_e32 v124, v111, v111
	v_mul_f32_e32 v125, v103, v103
	v_mul_f32_e32 v128, v113, v113
	v_mul_f32_e32 v129, v105, v105
	v_mul_f32_e32 v144, v107, v107
	v_mul_f32_e32 v145, v99, v99
	v_mul_f32_e32 v190, v109, v109
	v_mul_f32_e32 v191, v101, v101
	v_xor_b32_e32 v171, 16, v186
	v_add_u32_e32 v176, 64, v176
	v_fma_f32 v122, v110, v110, v124
	v_fma_f32 v123, v102, v102, v125
	v_fma_f32 v124, v112, v112, v128
	v_fma_f32 v125, v104, v104, v129
	v_fma_f32 v126, v106, v106, v144
	v_fma_f32 v127, v98, v98, v145
	v_fma_f32 v128, v108, v108, v190
	v_fma_f32 v129, v100, v100, v191
	v_cmp_lt_i32_e32 vcc, v171, v176
	v_pk_add_f32 v[122:123], v[122:123], v[124:125]
	v_pk_add_f32 v[124:125], v[126:127], v[128:129]
	v_cndmask_b32_e32 v142, v186, v171, vcc
	v_pk_add_f32 v[122:123], v[122:123], v[124:125]
	v_lshlrev_b32_e32 v126, 2, v142
	v_add_f32_e32 v122, v122, v123
	ds_bpermute_b32 v123, v126, v122
	v_xor_b32_e32 v124, 32, v186
	v_cmp_lt_i32_e32 vcc, v124, v176
	s_waitcnt lgkmcnt(0)
	v_add_f32_e32 v122, v122, v123
	v_cndmask_b32_e32 v124, v186, v124, vcc
	v_lshlrev_b32_e32 v124, 2, v124
	ds_bpermute_b32 v123, v124, v122
	s_waitcnt lgkmcnt(0)
	v_add_f32_e32 v122, v122, v123
	v_fmamk_f32 v122, v122, 0x3c800000, v183
	v_rsq_f32_e32 v122, v122
	s_nop 0
	v_mul_f32_e32 v122, v188, v122
	v_pk_mul_f32 v[124:125], v[110:111], v[122:123] op_sel_hi:[1,0]
	v_pk_mul_f32 v[126:127], v[112:113], v[122:123] op_sel_hi:[1,0]
	v_pk_mul_f32 v[142:143], v[106:107], v[122:123] op_sel_hi:[1,0]
	v_pk_mul_f32 v[144:145], v[108:109], v[122:123] op_sel_hi:[1,0]
	v_pk_mul_f32 v[178:179], v[102:103], v[122:123] op_sel_hi:[1,0]
	v_pk_mul_f32 v[190:191], v[104:105], v[122:123] op_sel_hi:[1,0]
	v_pk_mul_f32 v[192:193], v[98:99], v[122:123] op_sel_hi:[1,0]
	v_pk_mul_f32 v[194:195], v[100:101], v[122:123] op_sel_hi:[1,0]
	s_waitcnt vmcnt(3)
	v_pk_mul_f32 v[128:129], v[116:117], v[126:127]
	v_pk_mul_f32 v[126:127], v[114:115], v[124:125]
	s_waitcnt vmcnt(2)
	v_pk_mul_f32 v[124:125], v[120:121], v[144:145]
	v_pk_mul_f32 v[122:123], v[118:119], v[142:143]
	s_waitcnt vmcnt(1)
	v_pk_mul_f32 v[116:117], v[136:137], v[190:191]
	v_pk_mul_f32 v[114:115], v[134:135], v[178:179]
	s_waitcnt vmcnt(0)
	v_pk_mul_f32 v[120:121], v[140:141], v[194:195]
	v_pk_mul_f32 v[118:119], v[138:139], v[192:193]

; __device__ __forceinline__ float sq4(f32x4 v) { return (v[0] * v[0] + v[1] * v[1]) + (v[2] * v[2] + v[3] * v[3]); }
;     __device__ __forceinline__ void apply(int row, int cl, const Pre& P_, f32x4 a0, f32x4 a1, f32x4 b0, f32x4 b1) const {
;     ...
;             if (sel < 2) {
;                 float ss = (sq4(a0) + sq4(a1)) + (sq4(b0) + sq4(b1));
;                 ss += __shfl_xor(ss, 16); ss += __shfl_xor(ss, 32);
;                 const float rr = __builtin_amdgcn_rsqf(ss * (1.f / 64.f) + EPS) * (sel == 0 ? 0.125f * LOG2E : 1.f);
;                 const float* gp = qg + sel * (kg - qg) + (cl & 63);
;                 const f32x4 g0 = *(const f32x4*)gp, g1 = *(const f32x4*)(gp + 4), g2 = *(const f32x4*)(gp + 32), g3 = *(const f32x4*)(gp + 36);
;                 a0 = a0 * rr * g0; a1 = a1 * rr * g1; b0 = b0 * rr * g2; b1 = b1 * rr * g3;
.LBB0_235:
	s_andn2_b64 vcc, exec, s[46:47]
	s_cbranch_vccnz .LBB0_242
	v_mov_b64_e32 v[104:105], v[84:85]
	v_mov_b64_e32 v[100:101], v[88:89]
	v_mov_b64_e32 v[108:109], v[92:93]
	v_mov_b64_e32 v[112:113], v[96:97]
	v_mov_b64_e32 v[102:103], v[82:83]
	v_mov_b64_e32 v[98:99], v[86:87]
	v_mov_b64_e32 v[106:107], v[90:91]
	v_mov_b64_e32 v[110:111], v[94:95]
	s_and_saveexec_b64 s[46:47], s[6:7]
	s_cbranch_execz .LBB0_238
	v_mad_u64_u32 v[98:99], s[38:39], s28, v189, 0
	v_mov_b32_e32 v100, v99
	v_mad_u64_u32 v[100:101], s[38:39], s29, v189, v[100:101]
	v_mov_b32_e32 v99, v100
	v_lshl_add_u64 v[106:107], v[98:99], 2, v[156:157]
	global_load_dwordx4 v[98:101], v[106:107], off
	global_load_dwordx4 v[102:105], v[106:107], off offset:16
	global_load_dwordx4 v[116:119], v[106:107], off offset:128
	global_load_dwordx4 v[120:123], v[106:107], off offset:144
	v_and_b32_e32 v135, 64, v186
	v_mul_f32_e32 v108, v95, v95
	v_mul_f32_e32 v109, v87, v87
	v_mul_f32_e32 v112, v97, v97
	v_mul_f32_e32 v113, v89, v89
	v_mul_f32_e32 v126, v91, v91
	v_mul_f32_e32 v127, v83, v83
	v_mul_f32_e32 v132, v93, v93
	v_mul_f32_e32 v133, v85, v85
	v_xor_b32_e32 v134, 16, v186
	v_add_u32_e32 v135, 64, v135
	v_fma_f32 v106, v94, v94, v108
	v_fma_f32 v107, v86, v86, v109
	v_fma_f32 v108, v96, v96, v112
	v_fma_f32 v109, v88, v88, v113
	v_fma_f32 v110, v90, v90, v126
	v_fma_f32 v111, v82, v82, v127
	v_fma_f32 v112, v92, v92, v132
	v_fma_f32 v113, v84, v84, v133
	v_cmp_lt_i32_e32 vcc, v134, v135
	v_pk_add_f32 v[106:107], v[106:107], v[108:109]
	v_pk_add_f32 v[108:109], v[110:111], v[112:113]
	v_cndmask_b32_e32 v124, v186, v134, vcc
	v_pk_add_f32 v[106:107], v[106:107], v[108:109]
	v_lshlrev_b32_e32 v110, 2, v124
	v_add_f32_e32 v106, v106, v107
	ds_bpermute_b32 v107, v110, v106
	v_xor_b32_e32 v108, 32, v186
	v_cmp_lt_i32_e32 vcc, v108, v135
	s_waitcnt lgkmcnt(0)
	v_add_f32_e32 v106, v106, v107
	v_cndmask_b32_e32 v108, v186, v108, vcc
	v_lshlrev_b32_e32 v108, 2, v108
	ds_bpermute_b32 v107, v108, v106
	s_waitcnt lgkmcnt(0)
	v_add_f32_e32 v106, v106, v107
	v_fmamk_f32 v106, v106, 0x3c800000, v183
	v_rsq_f32_e32 v106, v106
	s_nop 0
	v_mul_f32_e32 v106, v188, v106
	v_pk_mul_f32 v[108:109], v[94:95], v[106:107] op_sel_hi:[1,0]
	v_pk_mul_f32 v[110:111], v[96:97], v[106:107] op_sel_hi:[1,0]
	v_pk_mul_f32 v[124:125], v[90:91], v[106:107] op_sel_hi:[1,0]
	v_pk_mul_f32 v[126:127], v[92:93], v[106:107] op_sel_hi:[1,0]
	v_pk_mul_f32 v[128:129], v[86:87], v[106:107] op_sel_hi:[1,0]
	v_pk_mul_f32 v[132:133], v[88:89], v[106:107] op_sel_hi:[1,0]
	v_pk_mul_f32 v[134:135], v[82:83], v[106:107] op_sel_hi:[1,0]
	v_pk_mul_f32 v[136:137], v[84:85], v[106:107] op_sel_hi:[1,0]
	s_waitcnt vmcnt(3)
	v_pk_mul_f32 v[112:113], v[100:101], v[110:111]
	v_pk_mul_f32 v[110:111], v[98:99], v[108:109]
	s_waitcnt vmcnt(2)
	v_pk_mul_f32 v[108:109], v[104:105], v[126:127]
	v_pk_mul_f32 v[106:107], v[102:103], v[124:125]
	s_waitcnt vmcnt(1)
	v_pk_mul_f32 v[100:101], v[118:119], v[132:133]
	v_pk_mul_f32 v[98:99], v[116:117], v[128:129]
	s_waitcnt vmcnt(0)
	v_pk_mul_f32 v[104:105], v[122:123], v[136:137]
	v_pk_mul_f32 v[102:103], v[120:121], v[134:135]

; __device__ __forceinline__ float sq4(f32x4 v) { return (v[0] * v[0] + v[1] * v[1]) + (v[2] * v[2] + v[3] * v[3]); }
;     __device__ __forceinline__ void apply(int row, int cl, const Pre& P_, f32x4 a0, f32x4 a1, f32x4 b0, f32x4 b1) const {
;     ...
;             if (sel < 2) {
;                 float ss = (sq4(a0) + sq4(a1)) + (sq4(b0) + sq4(b1));
;                 ss += __shfl_xor(ss, 16); ss += __shfl_xor(ss, 32);
;                 const float rr = __builtin_amdgcn_rsqf(ss * (1.f / 64.f) + EPS) * (sel == 0 ? 0.125f * LOG2E : 1.f);
;                 const float* gp = qg + sel * (kg - qg) + (cl & 63);
;                 const f32x4 g0 = *(const f32x4*)gp, g1 = *(const f32x4*)(gp + 4), g2 = *(const f32x4*)(gp + 32), g3 = *(const f32x4*)(gp + 36);
;                 a0 = a0 * rr * g0; a1 = a1 * rr * g1; b0 = b0 * rr * g2; b1 = b1 * rr * g3;
.LBB0_251:
	s_andn2_b64 vcc, exec, s[46:47]
	s_cbranch_vccnz .LBB0_258
	v_mov_b64_e32 v[88:89], v[68:69]
	v_mov_b64_e32 v[84:85], v[72:73]
	v_mov_b64_e32 v[92:93], v[76:77]
	v_mov_b64_e32 v[96:97], v[80:81]
	v_mov_b64_e32 v[86:87], v[66:67]
	v_mov_b64_e32 v[82:83], v[70:71]
	v_mov_b64_e32 v[90:91], v[74:75]
	v_mov_b64_e32 v[94:95], v[78:79]
	s_and_saveexec_b64 s[46:47], s[6:7]
	s_cbranch_execz .LBB0_254
	v_mad_u64_u32 v[82:83], s[38:39], s28, v189, 0
	v_mov_b32_e32 v84, v83
	v_mad_u64_u32 v[84:85], s[38:39], s29, v189, v[84:85]
	v_mov_b32_e32 v83, v84
	v_lshl_add_u64 v[90:91], v[82:83], 2, v[156:157]
	global_load_dwordx4 v[82:85], v[90:91], off
	global_load_dwordx4 v[86:89], v[90:91], off offset:16
	global_load_dwordx4 v[100:103], v[90:91], off offset:128
	global_load_dwordx4 v[104:107], v[90:91], off offset:144
	v_and_b32_e32 v117, 64, v186
	v_mul_f32_e32 v92, v79, v79
	v_mul_f32_e32 v93, v71, v71
	v_mul_f32_e32 v96, v81, v81
	v_mul_f32_e32 v97, v73, v73
	v_mul_f32_e32 v110, v75, v75
	v_mul_f32_e32 v111, v67, v67
	v_mul_f32_e32 v114, v77, v77
	v_mul_f32_e32 v115, v69, v69
	v_xor_b32_e32 v116, 16, v186
	v_add_u32_e32 v117, 64, v117
	v_fma_f32 v90, v78, v78, v92
	v_fma_f32 v91, v70, v70, v93
	v_fma_f32 v92, v80, v80, v96
	v_fma_f32 v93, v72, v72, v97
	v_fma_f32 v94, v74, v74, v110
	v_fma_f32 v95, v66, v66, v111
	v_fma_f32 v96, v76, v76, v114
	v_fma_f32 v97, v68, v68, v115
	v_cmp_lt_i32_e32 vcc, v116, v117
	v_pk_add_f32 v[90:91], v[90:91], v[92:93]
	v_pk_add_f32 v[92:93], v[94:95], v[96:97]
	v_cndmask_b32_e32 v108, v186, v116, vcc
	v_pk_add_f32 v[90:91], v[90:91], v[92:93]
	v_lshlrev_b32_e32 v94, 2, v108
	v_add_f32_e32 v90, v90, v91
	ds_bpermute_b32 v91, v94, v90
	v_xor_b32_e32 v92, 32, v186
	v_cmp_lt_i32_e32 vcc, v92, v117
	s_waitcnt lgkmcnt(0)
	v_add_f32_e32 v90, v90, v91
	v_cndmask_b32_e32 v92, v186, v92, vcc
	v_lshlrev_b32_e32 v92, 2, v92
	ds_bpermute_b32 v91, v92, v90
	s_waitcnt lgkmcnt(0)
	v_add_f32_e32 v90, v90, v91
	v_fmamk_f32 v90, v90, 0x3c800000, v183
	v_rsq_f32_e32 v90, v90
	s_nop 0
	v_mul_f32_e32 v90, v188, v90
	v_pk_mul_f32 v[92:93], v[78:79], v[90:91] op_sel_hi:[1,0]
	v_pk_mul_f32 v[94:95], v[80:81], v[90:91] op_sel_hi:[1,0]
	v_pk_mul_f32 v[108:109], v[74:75], v[90:91] op_sel_hi:[1,0]
	v_pk_mul_f32 v[110:111], v[76:77], v[90:91] op_sel_hi:[1,0]
	v_pk_mul_f32 v[112:113], v[70:71], v[90:91] op_sel_hi:[1,0]
	v_pk_mul_f32 v[114:115], v[72:73], v[90:91] op_sel_hi:[1,0]
	v_pk_mul_f32 v[116:117], v[66:67], v[90:91] op_sel_hi:[1,0]
	v_pk_mul_f32 v[118:119], v[68:69], v[90:91] op_sel_hi:[1,0]
	s_waitcnt vmcnt(3)
	v_pk_mul_f32 v[96:97], v[84:85], v[94:95]
	v_pk_mul_f32 v[94:95], v[82:83], v[92:93]
	s_waitcnt vmcnt(2)
	v_pk_mul_f32 v[92:93], v[88:89], v[110:111]
	v_pk_mul_f32 v[90:91], v[86:87], v[108:109]
	s_waitcnt vmcnt(1)
	v_pk_mul_f32 v[84:85], v[102:103], v[114:115]
	v_pk_mul_f32 v[82:83], v[100:101], v[112:113]
	s_waitcnt vmcnt(0)
	v_pk_mul_f32 v[88:89], v[106:107], v[118:119]
	v_pk_mul_f32 v[86:87], v[104:105], v[116:117]

; __device__ __forceinline__ float sq4(f32x4 v) { return (v[0] * v[0] + v[1] * v[1]) + (v[2] * v[2] + v[3] * v[3]); }
;     __device__ __forceinline__ void apply(int row, int cl, const Pre& P_, f32x4 a0, f32x4 a1, f32x4 b0, f32x4 b1) const {
;     ...
;             if (sel < 2) {
;                 float ss = (sq4(a0) + sq4(a1)) + (sq4(b0) + sq4(b1));
;                 ss += __shfl_xor(ss, 16); ss += __shfl_xor(ss, 32);
;                 const float rr = __builtin_amdgcn_rsqf(ss * (1.f / 64.f) + EPS) * (sel == 0 ? 0.125f * LOG2E : 1.f);
;                 const float* gp = qg + sel * (kg - qg) + (cl & 63);
;                 const f32x4 g0 = *(const f32x4*)gp, g1 = *(const f32x4*)(gp + 4), g2 = *(const f32x4*)(gp + 32), g3 = *(const f32x4*)(gp + 36);
;                 a0 = a0 * rr * g0; a1 = a1 * rr * g1; b0 = b0 * rr * g2; b1 = b1 * rr * g3;
.LBB0_267:
	s_andn2_b64 vcc, exec, s[46:47]
	s_cbranch_vccnz .LBB0_274
	v_mov_b64_e32 v[72:73], v[52:53]
	v_mov_b64_e32 v[68:69], v[56:57]
	v_mov_b64_e32 v[76:77], v[60:61]
	v_mov_b64_e32 v[80:81], v[64:65]
	v_mov_b64_e32 v[70:71], v[50:51]
	v_mov_b64_e32 v[66:67], v[54:55]
	v_mov_b64_e32 v[74:75], v[58:59]
	v_mov_b64_e32 v[78:79], v[62:63]
	s_and_saveexec_b64 s[46:47], s[6:7]
	s_cbranch_execz .LBB0_270
	v_mad_u64_u32 v[66:67], s[38:39], s28, v189, 0
	v_mov_b32_e32 v68, v67
	v_mad_u64_u32 v[68:69], s[38:39], s29, v189, v[68:69]
	v_mov_b32_e32 v67, v68
	v_lshl_add_u64 v[74:75], v[66:67], 2, v[156:157]
	global_load_dwordx4 v[66:69], v[74:75], off
	global_load_dwordx4 v[70:73], v[74:75], off offset:16
	global_load_dwordx4 v[90:93], v[74:75], off offset:128
	global_load_dwordx4 v[94:97], v[74:75], off offset:144
	v_and_b32_e32 v89, 64, v186
	v_mul_f32_e32 v76, v63, v63
	v_mul_f32_e32 v77, v55, v55
	v_mul_f32_e32 v80, v65, v65
	v_mul_f32_e32 v81, v57, v57
	v_mul_f32_e32 v98, v59, v59
	v_mul_f32_e32 v99, v51, v51
	v_mul_f32_e32 v102, v61, v61
	v_mul_f32_e32 v103, v53, v53
	v_xor_b32_e32 v83, 16, v186
	v_add_u32_e32 v89, 64, v89
	v_fma_f32 v74, v62, v62, v76
	v_fma_f32 v75, v54, v54, v77
	v_fma_f32 v76, v64, v64, v80
	v_fma_f32 v77, v56, v56, v81
	v_fma_f32 v78, v58, v58, v98
	v_fma_f32 v79, v50, v50, v99
	v_fma_f32 v80, v60, v60, v102
	v_fma_f32 v81, v52, v52, v103
	v_cmp_lt_i32_e32 vcc, v83, v89
	v_pk_add_f32 v[74:75], v[74:75], v[76:77]
	v_pk_add_f32 v[76:77], v[78:79], v[80:81]
	v_cndmask_b32_e32 v83, v186, v83, vcc
	v_pk_add_f32 v[74:75], v[74:75], v[76:77]
	v_lshlrev_b32_e32 v78, 2, v83
	v_add_f32_e32 v74, v74, v75
	ds_bpermute_b32 v75, v78, v74
	v_xor_b32_e32 v76, 32, v186
	v_cmp_lt_i32_e32 vcc, v76, v89
	s_waitcnt lgkmcnt(0)
	v_add_f32_e32 v74, v74, v75
	v_cndmask_b32_e32 v76, v186, v76, vcc
	v_lshlrev_b32_e32 v76, 2, v76
	ds_bpermute_b32 v75, v76, v74
	s_waitcnt lgkmcnt(0)
	v_add_f32_e32 v74, v74, v75
	v_fmamk_f32 v74, v74, 0x3c800000, v183
	v_rsq_f32_e32 v74, v74
	s_nop 0
	v_mul_f32_e32 v74, v188, v74
	v_pk_mul_f32 v[76:77], v[62:63], v[74:75] op_sel_hi:[1,0]
	v_pk_mul_f32 v[78:79], v[64:65], v[74:75] op_sel_hi:[1,0]
	v_pk_mul_f32 v[86:87], v[58:59], v[74:75] op_sel_hi:[1,0]
	v_pk_mul_f32 v[98:99], v[60:61], v[74:75] op_sel_hi:[1,0]
	v_pk_mul_f32 v[100:101], v[54:55], v[74:75] op_sel_hi:[1,0]
	v_pk_mul_f32 v[102:103], v[56:57], v[74:75] op_sel_hi:[1,0]
	v_pk_mul_f32 v[104:105], v[50:51], v[74:75] op_sel_hi:[1,0]
	v_pk_mul_f32 v[106:107], v[52:53], v[74:75] op_sel_hi:[1,0]
	s_waitcnt vmcnt(3)
	v_pk_mul_f32 v[80:81], v[68:69], v[78:79]
	v_pk_mul_f32 v[78:79], v[66:67], v[76:77]
	s_waitcnt vmcnt(2)
	v_pk_mul_f32 v[76:77], v[72:73], v[98:99]
	v_pk_mul_f32 v[74:75], v[70:71], v[86:87]
	s_waitcnt vmcnt(1)
	v_pk_mul_f32 v[68:69], v[92:93], v[102:103]
	v_pk_mul_f32 v[66:67], v[90:91], v[100:101]
	s_waitcnt vmcnt(0)
	v_pk_mul_f32 v[72:73], v[96:97], v[106:107]
	v_pk_mul_f32 v[70:71], v[94:95], v[104:105]

; __device__ __forceinline__ float sq4(f32x4 v) { return (v[0] * v[0] + v[1] * v[1]) + (v[2] * v[2] + v[3] * v[3]); }
;     __device__ __forceinline__ void apply(int row, int cl, const Pre& P_, f32x4 a0, f32x4 a1, f32x4 b0, f32x4 b1) const {
;     ...
;             if (sel < 2) {
;                 float ss = (sq4(a0) + sq4(a1)) + (sq4(b0) + sq4(b1));
;                 ss += __shfl_xor(ss, 16); ss += __shfl_xor(ss, 32);
;                 const float rr = __builtin_amdgcn_rsqf(ss * (1.f / 64.f) + EPS) * (sel == 0 ? 0.125f * LOG2E : 1.f);
;                 const float* gp = qg + sel * (kg - qg) + (cl & 63);
;                 const f32x4 g0 = *(const f32x4*)gp, g1 = *(const f32x4*)(gp + 4), g2 = *(const f32x4*)(gp + 32), g3 = *(const f32x4*)(gp + 36);
;                 a0 = a0 * rr * g0; a1 = a1 * rr * g1; b0 = b0 * rr * g2; b1 = b1 * rr * g3;
.LBB0_283:
	s_andn2_b64 vcc, exec, s[46:47]
	s_cbranch_vccnz .LBB0_290
	v_mov_b64_e32 v[56:57], v[36:37]
	v_mov_b64_e32 v[52:53], v[40:41]
	v_mov_b64_e32 v[60:61], v[44:45]
	v_mov_b64_e32 v[64:65], v[48:49]
	v_mov_b64_e32 v[54:55], v[34:35]
	v_mov_b64_e32 v[50:51], v[38:39]
	v_mov_b64_e32 v[58:59], v[42:43]
	v_mov_b64_e32 v[62:63], v[46:47]
	s_and_saveexec_b64 s[46:47], s[6:7]
	s_cbranch_execz .LBB0_286
	v_mad_u64_u32 v[50:51], s[38:39], s28, v189, 0
	v_mov_b32_e32 v52, v51
	v_mad_u64_u32 v[52:53], s[38:39], s29, v189, v[52:53]
	v_mov_b32_e32 v51, v52
	v_lshl_add_u64 v[58:59], v[50:51], 2, v[156:157]
	global_load_dwordx4 v[50:53], v[58:59], off
	global_load_dwordx4 v[54:57], v[58:59], off offset:16
	global_load_dwordx4 v[72:75], v[58:59], off offset:128
	global_load_dwordx4 v[76:79], v[58:59], off offset:144
	v_and_b32_e32 v83, 64, v186
	v_mul_f32_e32 v60, v47, v47
	v_mul_f32_e32 v61, v39, v39
	v_mul_f32_e32 v64, v49, v49
	v_mul_f32_e32 v65, v41, v41
	v_mul_f32_e32 v80, v43, v43
	v_mul_f32_e32 v81, v35, v35
	v_mul_f32_e32 v88, v45, v45
	v_mul_f32_e32 v89, v37, v37
	v_xor_b32_e32 v71, 16, v186
	v_add_u32_e32 v83, 64, v83
	v_fma_f32 v58, v46, v46, v60
	v_fma_f32 v59, v38, v38, v61
	v_fma_f32 v60, v48, v48, v64
	v_fma_f32 v61, v40, v40, v65
	v_fma_f32 v62, v42, v42, v80
	v_fma_f32 v63, v34, v34, v81
	v_fma_f32 v64, v44, v44, v88
	v_fma_f32 v65, v36, v36, v89
	v_cmp_lt_i32_e32 vcc, v71, v83
	v_pk_add_f32 v[58:59], v[58:59], v[60:61]
	v_pk_add_f32 v[60:61], v[62:63], v[64:65]
	v_cndmask_b32_e32 v68, v186, v71, vcc
	v_pk_add_f32 v[58:59], v[58:59], v[60:61]
	v_lshlrev_b32_e32 v62, 2, v68
	v_add_f32_e32 v58, v58, v59
	ds_bpermute_b32 v59, v62, v58
	v_xor_b32_e32 v60, 32, v186
	v_cmp_lt_i32_e32 vcc, v60, v83
	s_waitcnt lgkmcnt(0)
	v_add_f32_e32 v58, v58, v59
	v_cndmask_b32_e32 v60, v186, v60, vcc
	v_lshlrev_b32_e32 v60, 2, v60
	ds_bpermute_b32 v59, v60, v58
	s_waitcnt lgkmcnt(0)
	v_add_f32_e32 v58, v58, v59
	v_fmamk_f32 v58, v58, 0x3c800000, v183
	v_rsq_f32_e32 v58, v58
	s_nop 0
	v_mul_f32_e32 v58, v188, v58
	v_pk_mul_f32 v[60:61], v[46:47], v[58:59] op_sel_hi:[1,0]
	v_pk_mul_f32 v[62:63], v[48:49], v[58:59] op_sel_hi:[1,0]
	v_pk_mul_f32 v[68:69], v[42:43], v[58:59] op_sel_hi:[1,0]
	v_pk_mul_f32 v[80:81], v[44:45], v[58:59] op_sel_hi:[1,0]
	v_pk_mul_f32 v[86:87], v[38:39], v[58:59] op_sel_hi:[1,0]
	v_pk_mul_f32 v[88:89], v[40:41], v[58:59] op_sel_hi:[1,0]
	v_pk_mul_f32 v[90:91], v[34:35], v[58:59] op_sel_hi:[1,0]
	v_pk_mul_f32 v[92:93], v[36:37], v[58:59] op_sel_hi:[1,0]
	s_waitcnt vmcnt(3)
	v_pk_mul_f32 v[64:65], v[52:53], v[62:63]
	v_pk_mul_f32 v[62:63], v[50:51], v[60:61]
	s_waitcnt vmcnt(2)
	v_pk_mul_f32 v[60:61], v[56:57], v[80:81]
	v_pk_mul_f32 v[58:59], v[54:55], v[68:69]
	s_waitcnt vmcnt(1)
	v_pk_mul_f32 v[52:53], v[74:75], v[88:89]
	v_pk_mul_f32 v[50:51], v[72:73], v[86:87]
	s_waitcnt vmcnt(0)
	v_pk_mul_f32 v[56:57], v[78:79], v[92:93]
	v_pk_mul_f32 v[54:55], v[76:77], v[90:91]

; __device__ __forceinline__ float sq4(f32x4 v) { return (v[0] * v[0] + v[1] * v[1]) + (v[2] * v[2] + v[3] * v[3]); }
;     __device__ __forceinline__ void apply(int row, int cl, const Pre& P_, f32x4 a0, f32x4 a1, f32x4 b0, f32x4 b1) const {
;     ...
;             if (sel < 2) {
;                 float ss = (sq4(a0) + sq4(a1)) + (sq4(b0) + sq4(b1));
;                 ss += __shfl_xor(ss, 16); ss += __shfl_xor(ss, 32);
;                 const float rr = __builtin_amdgcn_rsqf(ss * (1.f / 64.f) + EPS) * (sel == 0 ? 0.125f * LOG2E : 1.f);
;                 const float* gp = qg + sel * (kg - qg) + (cl & 63);
;                 const f32x4 g0 = *(const f32x4*)gp, g1 = *(const f32x4*)(gp + 4), g2 = *(const f32x4*)(gp + 32), g3 = *(const f32x4*)(gp + 36);
;                 a0 = a0 * rr * g0; a1 = a1 * rr * g1; b0 = b0 * rr * g2; b1 = b1 * rr * g3;
.LBB0_299:
	s_andn2_b64 vcc, exec, s[46:47]
	s_cbranch_vccnz .LBB0_306
	v_mov_b64_e32 v[40:41], v[20:21]
	v_mov_b64_e32 v[36:37], v[24:25]
	v_mov_b64_e32 v[44:45], v[28:29]
	v_mov_b64_e32 v[48:49], v[32:33]
	v_mov_b64_e32 v[38:39], v[18:19]
	v_mov_b64_e32 v[34:35], v[22:23]
	v_mov_b64_e32 v[42:43], v[26:27]
	v_mov_b64_e32 v[46:47], v[30:31]
	s_and_saveexec_b64 s[46:47], s[6:7]
	s_cbranch_execz .LBB0_302
	v_mad_u64_u32 v[34:35], s[38:39], s28, v189, 0
	v_mov_b32_e32 v36, v35
	v_mad_u64_u32 v[36:37], s[38:39], s29, v189, v[36:37]
	v_mov_b32_e32 v35, v36
	v_lshl_add_u64 v[42:43], v[34:35], 2, v[156:157]
	global_load_dwordx4 v[34:37], v[42:43], off
	global_load_dwordx4 v[38:41], v[42:43], off offset:16
	global_load_dwordx4 v[52:55], v[42:43], off offset:128
	global_load_dwordx4 v[56:59], v[42:43], off offset:144
	v_and_b32_e32 v70, 64, v186
	v_mul_f32_e32 v44, v31, v31
	v_mul_f32_e32 v45, v23, v23
	v_mul_f32_e32 v48, v33, v33
	v_mul_f32_e32 v49, v25, v25
	v_mul_f32_e32 v62, v27, v27
	v_mul_f32_e32 v63, v19, v19
	v_mul_f32_e32 v68, v29, v29
	v_mul_f32_e32 v69, v21, v21
	v_xor_b32_e32 v66, 16, v186
	v_add_u32_e32 v70, 64, v70
	v_fma_f32 v42, v30, v30, v44
	v_fma_f32 v43, v22, v22, v45
	v_fma_f32 v44, v32, v32, v48
	v_fma_f32 v45, v24, v24, v49
	v_fma_f32 v46, v26, v26, v62
	v_fma_f32 v47, v18, v18, v63
	v_fma_f32 v48, v28, v28, v68
	v_fma_f32 v49, v20, v20, v69
	v_cmp_lt_i32_e32 vcc, v66, v70
	v_pk_add_f32 v[42:43], v[42:43], v[44:45]
	v_pk_add_f32 v[44:45], v[46:47], v[48:49]
	v_cndmask_b32_e32 v60, v186, v66, vcc
	v_pk_add_f32 v[42:43], v[42:43], v[44:45]
	v_lshlrev_b32_e32 v46, 2, v60
	v_add_f32_e32 v42, v42, v43
	ds_bpermute_b32 v43, v46, v42
	v_xor_b32_e32 v44, 32, v186
	v_cmp_lt_i32_e32 vcc, v44, v70
	s_waitcnt lgkmcnt(0)
	v_add_f32_e32 v42, v42, v43
	v_cndmask_b32_e32 v44, v186, v44, vcc
	v_lshlrev_b32_e32 v44, 2, v44
	ds_bpermute_b32 v43, v44, v42
	s_waitcnt lgkmcnt(0)
	v_add_f32_e32 v42, v42, v43
	v_fmamk_f32 v42, v42, 0x3c800000, v183
	v_rsq_f32_e32 v42, v42
	s_nop 0
	v_mul_f32_e32 v42, v188, v42
	v_pk_mul_f32 v[44:45], v[30:31], v[42:43] op_sel_hi:[1,0]
	v_pk_mul_f32 v[46:47], v[32:33], v[42:43] op_sel_hi:[1,0]
	v_pk_mul_f32 v[60:61], v[26:27], v[42:43] op_sel_hi:[1,0]
	v_pk_mul_f32 v[62:63], v[28:29], v[42:43] op_sel_hi:[1,0]
	v_pk_mul_f32 v[64:65], v[22:23], v[42:43] op_sel_hi:[1,0]
	v_pk_mul_f32 v[68:69], v[24:25], v[42:43] op_sel_hi:[1,0]
	v_pk_mul_f32 v[70:71], v[18:19], v[42:43] op_sel_hi:[1,0]
	v_pk_mul_f32 v[72:73], v[20:21], v[42:43] op_sel_hi:[1,0]
	s_waitcnt vmcnt(3)
	v_pk_mul_f32 v[48:49], v[36:37], v[46:47]
	v_pk_mul_f32 v[46:47], v[34:35], v[44:45]
	s_waitcnt vmcnt(2)
	v_pk_mul_f32 v[44:45], v[40:41], v[62:63]
	v_pk_mul_f32 v[42:43], v[38:39], v[60:61]
	s_waitcnt vmcnt(1)
	v_pk_mul_f32 v[36:37], v[54:55], v[68:69]
	v_pk_mul_f32 v[34:35], v[52:53], v[64:65]
	s_waitcnt vmcnt(0)
	v_pk_mul_f32 v[40:41], v[58:59], v[72:73]
	v_pk_mul_f32 v[38:39], v[56:57], v[70:71]

; __device__ __forceinline__ float sq4(f32x4 v) { return (v[0] * v[0] + v[1] * v[1]) + (v[2] * v[2] + v[3] * v[3]); }
;     __device__ __forceinline__ void apply(int row, int cl, const Pre& P_, f32x4 a0, f32x4 a1, f32x4 b0, f32x4 b1) const {
;     ...
;             if (sel < 2) {
;                 float ss = (sq4(a0) + sq4(a1)) + (sq4(b0) + sq4(b1));
;                 ss += __shfl_xor(ss, 16); ss += __shfl_xor(ss, 32);
;                 const float rr = __builtin_amdgcn_rsqf(ss * (1.f / 64.f) + EPS) * (sel == 0 ? 0.125f * LOG2E : 1.f);
;                 const float* gp = qg + sel * (kg - qg) + (cl & 63);
;                 const f32x4 g0 = *(const f32x4*)gp, g1 = *(const f32x4*)(gp + 4), g2 = *(const f32x4*)(gp + 32), g3 = *(const f32x4*)(gp + 36);
;                 a0 = a0 * rr * g0; a1 = a1 * rr * g1; b0 = b0 * rr * g2; b1 = b1 * rr * g3;
.LBB0_317:
	s_andn2_b64 vcc, exec, s[8:9]
	s_cbranch_vccnz .LBB0_324
	v_mov_b64_e32 v[24:25], v[4:5]
	v_mov_b64_e32 v[20:21], v[8:9]
	v_mov_b64_e32 v[28:29], v[12:13]
	v_mov_b64_e32 v[32:33], v[16:17]
	v_mov_b64_e32 v[22:23], v[2:3]
	v_mov_b64_e32 v[18:19], v[6:7]
	v_mov_b64_e32 v[26:27], v[10:11]
	v_mov_b64_e32 v[30:31], v[14:15]
	s_and_saveexec_b64 s[8:9], s[6:7]
	s_cbranch_execz .LBB0_320
	v_mad_u64_u32 v[18:19], s[6:7], s28, v189, 0
	v_mov_b32_e32 v20, v19
	v_mad_u64_u32 v[20:21], s[6:7], s29, v189, v[20:21]
	v_mov_b32_e32 v19, v20
	v_lshl_add_u64 v[26:27], v[18:19], 2, v[156:157]
	global_load_dwordx4 v[18:21], v[26:27], off
	global_load_dwordx4 v[22:25], v[26:27], off offset:16
	global_load_dwordx4 v[38:41], v[26:27], off offset:128
	global_load_dwordx4 v[42:45], v[26:27], off offset:144
	v_and_b32_e32 v52, 64, v186
	v_mul_f32_e32 v28, v15, v15
	v_mul_f32_e32 v29, v7, v7
	v_mul_f32_e32 v32, v17, v17
	v_mul_f32_e32 v33, v9, v9
	v_mul_f32_e32 v46, v11, v11
	v_mul_f32_e32 v47, v3, v3
	v_mul_f32_e32 v50, v13, v13
	v_mul_f32_e32 v51, v5, v5
	v_xor_b32_e32 v37, 16, v186
	v_add_u32_e32 v52, 64, v52
	v_fma_f32 v26, v14, v14, v28
	v_fma_f32 v27, v6, v6, v29
	v_fma_f32 v28, v16, v16, v32
	v_fma_f32 v29, v8, v8, v33
	v_fma_f32 v30, v10, v10, v46
	v_fma_f32 v31, v2, v2, v47
	v_fma_f32 v32, v12, v12, v50
	v_fma_f32 v33, v4, v4, v51
	v_cmp_lt_i32_e32 vcc, v37, v52
	v_pk_add_f32 v[26:27], v[26:27], v[28:29]
	v_pk_add_f32 v[28:29], v[30:31], v[32:33]
	v_cndmask_b32_e32 v34, v186, v37, vcc
	v_pk_add_f32 v[26:27], v[26:27], v[28:29]
	v_lshlrev_b32_e32 v30, 2, v34
	v_add_f32_e32 v26, v26, v27
	ds_bpermute_b32 v27, v30, v26
	v_xor_b32_e32 v28, 32, v186
	v_cmp_lt_i32_e32 vcc, v28, v52
	s_waitcnt lgkmcnt(0)
	v_add_f32_e32 v26, v26, v27
	v_cndmask_b32_e32 v28, v186, v28, vcc
	v_lshlrev_b32_e32 v28, 2, v28
	ds_bpermute_b32 v27, v28, v26
	s_waitcnt lgkmcnt(0)
	v_add_f32_e32 v26, v26, v27
	v_fmamk_f32 v26, v26, 0x3c800000, v183
	v_rsq_f32_e32 v26, v26
	s_nop 0
	v_mul_f32_e32 v26, v188, v26
	v_pk_mul_f32 v[28:29], v[14:15], v[26:27] op_sel_hi:[1,0]
	v_pk_mul_f32 v[30:31], v[16:17], v[26:27] op_sel_hi:[1,0]
	v_pk_mul_f32 v[34:35], v[10:11], v[26:27] op_sel_hi:[1,0]
	v_pk_mul_f32 v[46:47], v[12:13], v[26:27] op_sel_hi:[1,0]
	v_pk_mul_f32 v[48:49], v[6:7], v[26:27] op_sel_hi:[1,0]
	v_pk_mul_f32 v[50:51], v[8:9], v[26:27] op_sel_hi:[1,0]
	v_pk_mul_f32 v[52:53], v[2:3], v[26:27] op_sel_hi:[1,0]
	v_pk_mul_f32 v[54:55], v[4:5], v[26:27] op_sel_hi:[1,0]
	s_waitcnt vmcnt(3)
	v_pk_mul_f32 v[32:33], v[20:21], v[30:31]
	v_pk_mul_f32 v[30:31], v[18:19], v[28:29]
	s_waitcnt vmcnt(2)
	v_pk_mul_f32 v[28:29], v[24:25], v[46:47]
	v_pk_mul_f32 v[26:27], v[22:23], v[34:35]
	s_waitcnt vmcnt(1)
	v_pk_mul_f32 v[20:21], v[40:41], v[50:51]
	v_pk_mul_f32 v[18:19], v[38:39], v[48:49]
	s_waitcnt vmcnt(0)
	v_pk_mul_f32 v[24:25], v[44:45], v[54:55]
	v_pk_mul_f32 v[22:23], v[42:43], v[52:53]
